# v35 + GEMM prologues: issue K-tile 1 staging loads before the first wait (vmcnt 2->8, barrier moved down)
# speedup vs baseline: 1.0013x; 1.0013x over previous
.LBB0_250:
	s_add_u32 s18, s96, 0x5500000
	s_addc_u32 s19, s97, 0
	s_add_u32 s20, s96, 0x3200000
	s_mov_b64 s[22:23], 0x80
	s_addc_u32 s21, s97, 0
	s_and_b32 s48, s5, 3
	s_add_i32 m0, s43, 0x18000
	v_lshl_add_u64 v[6:7], v[6:7], 0, s[22:23]
	s_lshl_b32 s1, s4, 13
	s_lshl_b32 s3, s48, 12
	global_load_lds_dwordx4 v[6:7], off
	v_lshl_add_u64 v[4:5], v[4:5], 0, s[22:23]
	s_add_i32 m0, s43, 0x1a000
	s_add_i32 s49, s43, 0x8000
	s_add_i32 s50, s43, 0xa000
	global_load_lds_dwordx4 v[4:5], off
	v_lshl_add_u64 v[0:1], v[0:1], 0, s[22:23]
	s_mov_b32 m0, s49
	s_add_u32 s8, s12, 0x40080
	global_load_lds_dwordx4 v[0:1], off
	v_lshl_add_u64 v[0:1], v[2:3], 0, s[22:23]
	s_mov_b32 m0, s50
	s_addc_u32 s9, s13, 0
	global_load_lds_dwordx4 v[0:1], off
	s_add_i32 m0, s43, 0x1c000
	v_lshl_add_u64 v[0:1], s[8:9], 0, v[194:195]
	global_load_lds_dwordx4 v[0:1], off
	v_lshl_add_u64 v[0:1], s[8:9], 0, v[198:199]
	s_add_i32 m0, s43, 0x1e000
	v_lshlrev_b32_e32 v3, 2, v226
	global_load_lds_dwordx4 v[0:1], off
	v_bfe_u32 v1, v226, 4, 2
	v_and_b32_e32 v0, 15, v226
	v_lshlrev_b32_e32 v2, 4, v1
	v_lshl_or_b32 v203, s4, 6, v0
	v_lshl_or_b32 v0, v0, 6, v2
	v_and_b32_e32 v3, 32, v3
	v_bitop3_b32 v4, v0, s1, v3 bitop3:0xde
	v_lshlrev_b32_e32 v0, 6, v226
	s_movk_i32 s1, 0x3c0
	v_and_or_b32 v0, v0, s1, v2
	v_lshlrev_b32_e32 v200, 5, v1
	v_lshlrev_b32_e32 v202, 3, v1
	v_bitop3_b32 v224, s3, v0, v3 bitop3:0xf6
	s_cmpk_lt_u32 s6, 0x100
	v_cmp_eq_u32_e64 s[4:5], 0, v1
	v_cmp_gt_u32_e64 s[6:7], 2, v1
	v_lshl_add_u64 v[0:1], s[96:97], 0, v[200:201]
	s_mov_b64 s[8:9], 0x2e00000
	v_lshl_add_u64 v[204:205], v[0:1], 0, s[8:9]
	v_lshlrev_b32_e32 v0, 8, v226
	v_and_b32_e32 v0, 0x38000, v0
	v_lshlrev_b32_e32 v1, 11, v10
	v_or3_b32 v0, v8, v0, v1
	v_add_u32_e32 v206, v0, v9
	v_lshlrev_b32_e32 v0, 4, v11
	v_and_b32_e32 v0, 0x78000, v0
	s_waitcnt vmcnt(8)
	s_barrier
	s_waitcnt vmcnt(6)
	v_or3_b32 v0, v8, v0, v1
	s_cselect_b64 s[24:25], -1, 0
	v_add_u32_e32 v208, v0, v9
	s_add_i32 s54, 0, 0x10000
	s_add_i32 s55, 0, 0x14000
	v_mbcnt_lo_u32_b32 v0, -1, 0
	s_ashr_i32 s51, s90, 31
	s_mov_b32 s52, s90
	s_ashr_i32 s53, s88, 31
	v_mov_b32_e32 v207, v201
	v_mov_b32_e32 v209, v201
	v_mov_b64_e32 v[210:211], 0x300
	v_mov_b64_e32 v[212:213], 0x2ff
	v_add_u32_e32 v225, s54, v224
	v_add_u32_e32 v228, s55, v224
	v_add_u32_e32 v229, 0, v4
	v_mov_b32_e32 v230, 0x358637bd
	s_mov_b32 s56, 0xf800000
	v_mov_b32_e32 v231, 0x260
	s_movk_i32 s57, 0x1800
	v_lshlrev_b32_e32 v214, 1, v202
	v_mov_b32_e32 v232, 0x3e38aa3b
	v_mov_b32_e32 v233, 0x3e000000
	v_mbcnt_hi_u32_b32 v234, -1, v0
	s_barrier
	s_branch .LBB0_253

.LBB0_610:
	v_bfe_u32 v133, v226, 4, 2
	s_lshl_b32 s6, s6, 5
	v_lshlrev_b32_e32 v11, 6, v226
	v_and_b32_e32 v193, 15, v226
	v_lshlrev_b32_e32 v9, 4, v133
	s_and_b32 s14, s6, 0x60
	v_and_b32_e32 v200, 0x3c0, v11
	v_lshl_or_b32 v132, s7, 6, v193
	v_lshl_or_b32 v194, v193, 6, v9
	s_lshl_b32 s7, s7, 13
	v_and_b32_e32 v199, 32, v125
	v_or_b32_e32 v11, v9, v200
	s_lshl_b32 s6, s14, 7
	v_bitop3_b32 v10, v194, s7, v199 bitop3:0xde
	v_bitop3_b32 v196, v9, v199, v200 bitop3:0x36
	v_bitop3_b32 v9, s6, v11, v199 bitop3:0xf6
	s_mov_b64 s[6:7], 0x80
	s_add_i32 m0, s16, 0x18000
	v_lshl_add_u64 v[6:7], v[6:7], 0, s[6:7]
	global_load_lds_dwordx4 v[6:7], off
	v_lshl_add_u64 v[4:5], v[4:5], 0, s[6:7]
	s_add_i32 m0, s16, 0x1a000
	s_add_i32 s20, s16, 0x8000
	s_add_i32 s21, s16, 0xa000
	global_load_lds_dwordx4 v[4:5], off
	v_lshl_add_u64 v[2:3], v[2:3], 0, s[6:7]
	s_mov_b32 m0, s20
	s_add_u32 s22, s2, 0x40080
	global_load_lds_dwordx4 v[2:3], off
	v_lshl_add_u64 v[0:1], v[0:1], 0, s[6:7]
	s_mov_b32 m0, s21
	s_addc_u32 s23, s3, 0
	global_load_lds_dwordx4 v[0:1], off
	s_add_i32 m0, s16, 0x1c000
	v_lshl_add_u64 v[0:1], s[22:23], 0, v[156:157]
	global_load_lds_dwordx4 v[0:1], off
	v_lshl_add_u64 v[0:1], s[22:23], 0, v[152:153]
	s_add_i32 m0, s16, 0x1e000
	v_lshrrev_b32_e32 v195, 7, v226
	global_load_lds_dwordx4 v[0:1], off
	v_lshlrev_b32_e32 v0, 15, v195
	v_lshlrev_b32_e32 v1, 11, v186
	v_readlane_b32 s48, v254, 0
	v_or3_b32 v0, v184, v0, v1
	v_readlane_b32 s50, v254, 2
	v_lshrrev_b32_e32 v197, 11, v8
	v_add_u32_e32 v160, v0, v185
	v_readlane_b32 s51, v254, 3
	s_add_u32 s10, s50, s10
	v_lshlrev_b32_e32 v0, 15, v197
	s_waitcnt vmcnt(8)
	s_barrier
	s_waitcnt vmcnt(6)
	s_addc_u32 s11, s51, s11
	v_or3_b32 v0, v184, v0, v1
	s_add_i32 s36, 0, 0x10000
	s_add_i32 s37, 0, 0x14000
	s_add_i32 s45, 0, 0x18000
	s_add_i32 s46, 0, 0x1c000
	v_mov_b32_e32 v161, v157
	v_add_u32_e32 v162, v0, v185
	v_mov_b32_e32 v163, v157
	s_add_i32 s30, s36, s12
	s_add_i32 s33, s37, s12
	s_add_i32 s35, s45, s12
	s_add_i32 s47, s46, s12
	s_mov_b64 s[8:9], 0x40080
	v_lshl_add_u64 v[128:129], s[10:11], 0, v[160:161]
	v_lshl_add_u64 v[130:131], s[10:11], 0, v[162:163]
	s_mov_b32 s22, -2
	v_add_u32_e32 v134, s36, v9
	v_add_u32_e32 v135, s37, v9
	v_add_u32_e32 v136, 0, v10
	s_add_i32 s23, s16, 0xc000
	s_add_i32 s29, s16, 0xe000
	s_add_i32 s31, s30, 0x2000
	s_add_i32 s34, s33, 0x2000
	v_add_u32_e32 v137, s45, v9
	v_add_u32_e32 v138, s46, v9
	s_add_i32 s41, s35, 0x2000
	s_add_i32 s48, s47, 0x2000
	v_mov_b32_e32 v0, v157
	v_mov_b32_e32 v1, v157
	v_mov_b32_e32 v2, v157
	v_mov_b32_e32 v3, v157
	v_mov_b32_e32 v4, v157
	v_mov_b32_e32 v5, v157
	v_mov_b32_e32 v6, v157
	v_mov_b32_e32 v7, v157
	v_mov_b32_e32 v16, v157
	v_mov_b32_e32 v17, v157
	v_mov_b32_e32 v18, v157
	v_mov_b32_e32 v19, v157
	v_mov_b32_e32 v20, v157
	v_mov_b32_e32 v21, v157
	v_mov_b32_e32 v22, v157
	v_mov_b32_e32 v23, v157
	v_mov_b32_e32 v32, v157
	v_mov_b32_e32 v33, v157
	v_mov_b32_e32 v34, v157
	v_mov_b32_e32 v35, v157
	v_mov_b32_e32 v36, v157
	v_mov_b32_e32 v37, v157
	v_mov_b32_e32 v38, v157
	v_mov_b32_e32 v39, v157
	v_mov_b32_e32 v48, v157
	v_mov_b32_e32 v49, v157
	v_mov_b32_e32 v50, v157
	v_mov_b32_e32 v51, v157
	v_mov_b32_e32 v52, v157
	v_mov_b32_e32 v53, v157
	v_mov_b32_e32 v54, v157
	v_mov_b32_e32 v55, v157
	v_mov_b32_e32 v8, v157
	v_mov_b32_e32 v9, v157
	v_mov_b32_e32 v10, v157
	v_mov_b32_e32 v11, v157
	v_mov_b32_e32 v12, v157
	v_mov_b32_e32 v13, v157
	v_mov_b32_e32 v14, v157
	v_mov_b32_e32 v15, v157
	v_mov_b32_e32 v24, v157
	v_mov_b32_e32 v25, v157
	v_mov_b32_e32 v26, v157
	v_mov_b32_e32 v27, v157
	v_mov_b32_e32 v28, v157
	v_mov_b32_e32 v29, v157
	v_mov_b32_e32 v30, v157
	v_mov_b32_e32 v31, v157
	v_mov_b32_e32 v40, v157
	v_mov_b32_e32 v41, v157
	v_mov_b32_e32 v42, v157
	v_mov_b32_e32 v43, v157
	v_mov_b32_e32 v44, v157
	v_mov_b32_e32 v45, v157
	v_mov_b32_e32 v46, v157
	v_mov_b32_e32 v47, v157
	v_mov_b32_e32 v56, v157
	v_mov_b32_e32 v57, v157
	v_mov_b32_e32 v58, v157
	v_mov_b32_e32 v59, v157
	v_mov_b32_e32 v60, v157
	v_mov_b32_e32 v61, v157
	v_mov_b32_e32 v62, v157
	v_mov_b32_e32 v63, v157
	v_mov_b32_e32 v64, v157
	v_mov_b32_e32 v65, v157
	v_mov_b32_e32 v66, v157
	v_mov_b32_e32 v67, v157
	v_mov_b32_e32 v68, v157
	v_mov_b32_e32 v69, v157
	v_mov_b32_e32 v70, v157
	v_mov_b32_e32 v71, v157
	v_mov_b32_e32 v80, v157
	v_mov_b32_e32 v81, v157
	v_mov_b32_e32 v82, v157
	v_mov_b32_e32 v83, v157
	v_mov_b32_e32 v84, v157
	v_mov_b32_e32 v85, v157
	v_mov_b32_e32 v86, v157
	v_mov_b32_e32 v87, v157
	v_mov_b32_e32 v96, v157
	v_mov_b32_e32 v97, v157
	v_mov_b32_e32 v98, v157
	v_mov_b32_e32 v99, v157
	v_mov_b32_e32 v100, v157
	v_mov_b32_e32 v101, v157
	v_mov_b32_e32 v102, v157
	v_mov_b32_e32 v103, v157
	v_mov_b32_e32 v112, v157
	v_mov_b32_e32 v113, v157
	v_mov_b32_e32 v114, v157
	v_mov_b32_e32 v115, v157
	v_mov_b32_e32 v116, v157
	v_mov_b32_e32 v117, v157
	v_mov_b32_e32 v118, v157
	v_mov_b32_e32 v119, v157
	v_mov_b32_e32 v72, v157
	v_mov_b32_e32 v73, v157
	v_mov_b32_e32 v74, v157
	v_mov_b32_e32 v75, v157
	v_mov_b32_e32 v76, v157
	v_mov_b32_e32 v77, v157
	v_mov_b32_e32 v78, v157
	v_mov_b32_e32 v79, v157
	v_mov_b32_e32 v88, v157
	v_mov_b32_e32 v89, v157
	v_mov_b32_e32 v90, v157
	v_mov_b32_e32 v91, v157
	v_mov_b32_e32 v92, v157
	v_mov_b32_e32 v93, v157
	v_mov_b32_e32 v94, v157
	v_mov_b32_e32 v95, v157
	v_mov_b32_e32 v104, v157
	v_mov_b32_e32 v105, v157
	v_mov_b32_e32 v106, v157
	v_mov_b32_e32 v107, v157
	v_mov_b32_e32 v108, v157
	v_mov_b32_e32 v109, v157
	v_mov_b32_e32 v110, v157
	v_mov_b32_e32 v111, v157
	v_mov_b32_e32 v120, v157
	v_mov_b32_e32 v121, v157
	v_mov_b32_e32 v122, v157
	v_mov_b32_e32 v123, v157
	v_mov_b32_e32 v124, v157
	v_mov_b32_e32 v125, v157
	v_mov_b32_e32 v126, v157
	v_mov_b32_e32 v127, v157
	s_barrier
	v_readlane_b32 s49, v254, 1

.LBB0_657:
	s_add_u32 s14, s96, 0x7500000
	s_addc_u32 s15, s97, 0
	s_lshl_b32 s2, s2, 5
	s_mov_b64 s[22:23], 0x80
	s_and_b32 s7, s2, 0x60
	s_add_i32 m0, s54, 0x18000
	v_lshl_add_u64 v[0:1], v[0:1], 0, s[22:23]
	s_lshl_b32 s58, s52, 2
	s_lshl_b32 s6, s1, 13
	s_lshl_b32 s28, s7, 7
	global_load_lds_dwordx4 v[0:1], off
	v_lshl_add_u64 v[0:1], v[2:3], 0, s[22:23]
	s_add_i32 m0, s54, 0x1a000
	s_add_i32 s59, s54, 0x8000
	s_add_i32 s60, s54, 0xa000
	global_load_lds_dwordx4 v[0:1], off
	v_lshl_add_u64 v[0:1], v[6:7], 0, s[22:23]
	s_mov_b32 m0, s59
	s_add_u32 s2, s16, 0x40080
	global_load_lds_dwordx4 v[0:1], off
	v_lshl_add_u64 v[0:1], v[4:5], 0, s[22:23]
	s_mov_b32 m0, s60
	s_addc_u32 s3, s17, 0
	global_load_lds_dwordx4 v[0:1], off
	s_add_i32 m0, s54, 0x1c000
	v_lshl_add_u64 v[0:1], s[2:3], 0, v[156:157]
	global_load_lds_dwordx4 v[0:1], off
	v_lshl_add_u64 v[0:1], s[2:3], 0, v[152:153]
	s_add_i32 m0, s54, 0x1e000
	v_lshlrev_b32_e32 v3, 2, v193
	global_load_lds_dwordx4 v[0:1], off
	v_lshrrev_b32_e32 v0, 1, v226
	v_and_b32_e32 v0, 24, v0
	v_lshlrev_b32_e32 v1, 1, v0
	v_lshl_or_b32 v2, v193, 6, v1
	v_and_b32_e32 v138, 32, v3
	v_or_b32_e32 v1, v1, v200
	s_waitcnt vmcnt(8)
	v_and_b32_e32 v250, 0xff, v226
	v_lshlrev_b32_e32 v250, 2, v250
	v_add_u32_e32 v250, 0x20200, v250
	ds_write_b32 v250, v251
	v_mov_b32_e32 v252, 0x20200
	s_waitcnt lgkmcnt(0)
	s_barrier
	s_waitcnt vmcnt(6)
	v_bitop3_b32 v2, v2, s6, v138 bitop3:0xde
	v_bitop3_b32 v140, s28, v1, v199 bitop3:0xf6
	s_cmpk_lt_u32 s0, 0x100
	v_lshl_or_b32 v139, s1, 6, v193
	s_cselect_b64 s[28:29], -1, 0
	v_or_b32_e32 v141, s7, v0
	v_add_u32_e32 v142, s36, v140
	v_add_u32_e32 v143, s37, v140
	v_add_u32_e32 v144, 0, v2
	v_mov_b32_e32 v145, 0x358637bd
	s_mov_b32 s61, 0xf800000
	v_mov_b32_e32 v146, 0x260
	s_mov_b32 s30, s58
	s_mov_b32 s34, s40
	s_mov_b32 s62, s41
	s_barrier
	s_branch .LBB0_660

.LBB0_683:
	v_lshl_or_b32 v140, s7, 6, v193
	s_lshl_b32 s7, s7, 13
	s_lshl_b32 s6, s6, 5
	v_bitop3_b32 v8, v194, s7, v138 bitop3:0xde
	s_and_b32 s23, s6, 0x60
	s_mov_b64 s[6:7], 0x80
	s_add_i32 m0, s19, 0x18000
	v_lshl_add_u64 v[6:7], v[6:7], 0, s[6:7]
	global_load_lds_dwordx4 v[6:7], off
	v_lshl_add_u64 v[4:5], v[4:5], 0, s[6:7]
	s_add_i32 m0, s19, 0x1a000
	s_add_i32 s28, s19, 0x8000
	s_add_i32 s29, s19, 0xa000
	global_load_lds_dwordx4 v[4:5], off
	v_lshl_add_u64 v[2:3], v[2:3], 0, s[6:7]
	s_mov_b32 m0, s28
	s_add_u32 s14, s0, 0x100080
	global_load_lds_dwordx4 v[2:3], off
	v_lshl_add_u64 v[0:1], v[0:1], 0, s[6:7]
	s_mov_b32 m0, s29
	s_addc_u32 s15, s1, 0
	global_load_lds_dwordx4 v[0:1], off
	s_add_i32 m0, s19, 0x1c000
	v_lshl_add_u64 v[0:1], s[14:15], 0, v[132:133]
	global_load_lds_dwordx4 v[0:1], off
	v_lshl_add_u64 v[0:1], s[14:15], 0, v[128:129]
	s_add_i32 m0, s19, 0x1e000
	s_add_i32 s12, s44, s53
	global_load_lds_dwordx4 v[0:1], off
	s_lshl_b64 s[12:13], s[12:13], 21
	v_lshlrev_b32_e32 v0, 17, v195
	v_lshlrev_b32_e32 v2, 13, v186
	v_or3_b32 v0, v184, v0, v2
	s_add_u32 s12, s96, s12
	v_add_u32_e32 v0, v0, v185
	v_mov_b32_e32 v1, v133
	s_addc_u32 s13, s97, s13
	v_lshl_add_u64 v[136:137], s[12:13], 0, v[0:1]
	v_lshlrev_b32_e32 v0, 17, v197
	v_lshl_or_b32 v9, s23, 7, v196
	s_waitcnt vmcnt(8)
	s_barrier
	s_waitcnt vmcnt(6)
	v_or3_b32 v0, v184, v0, v2
	v_add_u32_e32 v0, v0, v185
	v_add_u32_e32 v141, s36, v9
	s_add_i32 s34, s36, s16
	s_add_i32 s36, s37, s16
	v_add_u32_e32 v144, s45, v9
	s_add_i32 s41, s45, s16
	s_add_i32 s45, s46, s16
	v_lshl_add_u64 v[138:139], s[12:13], 0, v[0:1]
	s_mov_b32 s30, -2
	s_mov_b64 s[12:13], 0x7600080
	v_add_u32_e32 v142, s37, v9
	v_add_u32_e32 v143, 0, v8
	s_add_i32 s31, s19, 0xc000
	s_add_i32 s33, s19, 0xe000
	s_add_i32 s35, s34, 0x2000
	s_add_i32 s37, s36, 0x2000
	v_add_u32_e32 v145, s46, v9
	s_add_i32 s44, s41, 0x2000
	s_add_i32 s46, s45, 0x2000
	v_mov_b32_e32 v0, v133
	v_mov_b32_e32 v2, v133
	v_mov_b32_e32 v3, v133
	v_mov_b32_e32 v4, v133
	v_mov_b32_e32 v5, v133
	v_mov_b32_e32 v6, v133
	v_mov_b32_e32 v7, v133
	v_mov_b32_e32 v16, v133
	v_mov_b32_e32 v17, v133
	v_mov_b32_e32 v18, v133
	v_mov_b32_e32 v19, v133
	v_mov_b32_e32 v20, v133
	v_mov_b32_e32 v21, v133
	v_mov_b32_e32 v22, v133
	v_mov_b32_e32 v23, v133
	v_mov_b32_e32 v32, v133
	v_mov_b32_e32 v33, v133
	v_mov_b32_e32 v34, v133
	v_mov_b32_e32 v35, v133
	v_mov_b32_e32 v36, v133
	v_mov_b32_e32 v37, v133
	v_mov_b32_e32 v38, v133
	v_mov_b32_e32 v39, v133
	v_mov_b32_e32 v48, v133
	v_mov_b32_e32 v49, v133
	v_mov_b32_e32 v50, v133
	v_mov_b32_e32 v51, v133
	v_mov_b32_e32 v52, v133
	v_mov_b32_e32 v53, v133
	v_mov_b32_e32 v54, v133
	v_mov_b32_e32 v55, v133
	v_mov_b32_e32 v8, v133
	v_mov_b32_e32 v9, v133
	v_mov_b32_e32 v10, v133
	v_mov_b32_e32 v11, v133
	v_mov_b32_e32 v12, v133
	v_mov_b32_e32 v13, v133
	v_mov_b32_e32 v14, v133
	v_mov_b32_e32 v15, v133
	v_mov_b32_e32 v24, v133
	v_mov_b32_e32 v25, v133
	v_mov_b32_e32 v26, v133
	v_mov_b32_e32 v27, v133
	v_mov_b32_e32 v28, v133
	v_mov_b32_e32 v29, v133
	v_mov_b32_e32 v30, v133
	v_mov_b32_e32 v31, v133
	v_mov_b32_e32 v40, v133
	v_mov_b32_e32 v41, v133
	v_mov_b32_e32 v42, v133
	v_mov_b32_e32 v43, v133
	v_mov_b32_e32 v44, v133
	v_mov_b32_e32 v45, v133
	v_mov_b32_e32 v46, v133
	v_mov_b32_e32 v47, v133
	v_mov_b32_e32 v56, v133
	v_mov_b32_e32 v57, v133
	v_mov_b32_e32 v58, v133
	v_mov_b32_e32 v59, v133
	v_mov_b32_e32 v60, v133
	v_mov_b32_e32 v61, v133
	v_mov_b32_e32 v62, v133
	v_mov_b32_e32 v63, v133
	v_mov_b32_e32 v64, v133
	v_mov_b32_e32 v65, v133
	v_mov_b32_e32 v66, v133
	v_mov_b32_e32 v67, v133
	v_mov_b32_e32 v68, v133
	v_mov_b32_e32 v69, v133
	v_mov_b32_e32 v70, v133
	v_mov_b32_e32 v71, v133
	v_mov_b32_e32 v80, v133
	v_mov_b32_e32 v81, v133
	v_mov_b32_e32 v82, v133
	v_mov_b32_e32 v83, v133
	v_mov_b32_e32 v84, v133
	v_mov_b32_e32 v85, v133
	v_mov_b32_e32 v86, v133
	v_mov_b32_e32 v87, v133
	v_mov_b32_e32 v96, v133
	v_mov_b32_e32 v97, v133
	v_mov_b32_e32 v98, v133
	v_mov_b32_e32 v99, v133
	v_mov_b32_e32 v100, v133
	v_mov_b32_e32 v101, v133
	v_mov_b32_e32 v102, v133
	v_mov_b32_e32 v103, v133
	v_mov_b32_e32 v112, v133
	v_mov_b32_e32 v113, v133
	v_mov_b32_e32 v114, v133
	v_mov_b32_e32 v115, v133
	v_mov_b32_e32 v116, v133
	v_mov_b32_e32 v117, v133
	v_mov_b32_e32 v118, v133
	v_mov_b32_e32 v119, v133
	v_mov_b32_e32 v72, v133
	v_mov_b32_e32 v73, v133
	v_mov_b32_e32 v74, v133
	v_mov_b32_e32 v75, v133
	v_mov_b32_e32 v76, v133
	v_mov_b32_e32 v77, v133
	v_mov_b32_e32 v78, v133
	v_mov_b32_e32 v79, v133
	v_mov_b32_e32 v88, v133
	v_mov_b32_e32 v89, v133
	v_mov_b32_e32 v90, v133
	v_mov_b32_e32 v91, v133
	v_mov_b32_e32 v92, v133
	v_mov_b32_e32 v93, v133
	v_mov_b32_e32 v94, v133
	v_mov_b32_e32 v95, v133
	v_mov_b32_e32 v104, v133
	v_mov_b32_e32 v105, v133
	v_mov_b32_e32 v106, v133
	v_mov_b32_e32 v107, v133
	v_mov_b32_e32 v108, v133
	v_mov_b32_e32 v109, v133
	v_mov_b32_e32 v110, v133
	v_mov_b32_e32 v111, v133
	v_mov_b32_e32 v120, v133
	v_mov_b32_e32 v121, v133
	v_mov_b32_e32 v122, v133
	v_mov_b32_e32 v123, v133
	v_mov_b32_e32 v124, v133
	v_mov_b32_e32 v125, v133
	v_mov_b32_e32 v126, v133
	v_mov_b32_e32 v127, v133
	s_barrier

.LBB0_762:
	s_add_u32 s18, s96, 0x5500000
	s_addc_u32 s19, s97, 0
	s_add_u32 s20, s96, 0x20000
	s_addc_u32 s21, s97, 0
	s_add_u32 s22, s96, 0x3200000
	s_mov_b64 s[24:25], 0x80
	s_addc_u32 s23, s97, 0
	s_and_b32 s57, s5, 3
	s_add_i32 m0, s50, 0x18000
	v_lshl_add_u64 v[6:7], v[6:7], 0, s[24:25]
	s_lshl_b32 s1, s4, 13
	s_lshl_b32 s3, s57, 12
	global_load_lds_dwordx4 v[6:7], off
	v_lshl_add_u64 v[4:5], v[4:5], 0, s[24:25]
	s_add_i32 m0, s50, 0x1a000
	s_add_i32 s58, s50, 0x8000
	s_add_i32 s59, s50, 0xa000
	global_load_lds_dwordx4 v[4:5], off
	v_lshl_add_u64 v[0:1], v[0:1], 0, s[24:25]
	s_mov_b32 m0, s58
	s_add_u32 s8, s12, 0x40080
	global_load_lds_dwordx4 v[0:1], off
	v_lshl_add_u64 v[0:1], v[2:3], 0, s[24:25]
	s_mov_b32 m0, s59
	s_addc_u32 s9, s13, 0
	global_load_lds_dwordx4 v[0:1], off
	s_add_i32 m0, s50, 0x1c000
	v_lshl_add_u64 v[0:1], s[8:9], 0, v[196:197]
	global_load_lds_dwordx4 v[0:1], off
	v_lshl_add_u64 v[0:1], s[8:9], 0, v[200:201]
	s_add_i32 m0, s50, 0x1e000
	v_lshlrev_b32_e32 v3, 2, v226
	global_load_lds_dwordx4 v[0:1], off
	v_bfe_u32 v1, v226, 4, 2
	v_and_b32_e32 v0, 15, v226
	v_lshlrev_b32_e32 v2, 4, v1
	v_lshl_or_b32 v193, s4, 6, v0
	v_lshl_or_b32 v0, v0, 6, v2
	v_and_b32_e32 v3, 32, v3
	v_bitop3_b32 v0, v0, s1, v3 bitop3:0xde
	v_lshlrev_b32_e32 v4, 6, v226
	s_movk_i32 s1, 0x3c0
	v_lshlrev_b32_e32 v204, 3, v1
	v_and_or_b32 v2, v4, s1, v2
	s_cmpk_lt_u32 s6, 0x100
	v_cmp_eq_u32_e64 s[4:5], 0, v1
	v_cmp_gt_u32_e64 s[6:7], 2, v1
	v_lshlrev_b32_e32 v202, 5, v1
	v_lshlrev_b32_e32 v1, 8, v226
	v_bitop3_b32 v231, s3, v2, v3 bitop3:0xf6
	v_and_b32_e32 v1, 0x38000, v1
	v_lshlrev_b32_e32 v2, 11, v10
	v_or3_b32 v1, v8, v1, v2
	v_add_u32_e32 v208, v1, v9
	v_lshlrev_b32_e32 v1, 4, v11
	s_waitcnt vmcnt(8)
	s_barrier
	s_waitcnt vmcnt(6)
	v_and_b32_e32 v1, 0x78000, v1
	s_cselect_b64 s[26:27], -1, 0
	v_or3_b32 v1, v8, v1, v2
	s_add_i32 s63, 0, 0x10000
	s_add_i32 s64, 0, 0x14000
	v_add_u32_e32 v234, 0, v0
	v_mbcnt_lo_u32_b32 v0, -1, 0
	s_ashr_i32 s60, s90, 31
	s_mov_b32 s61, s90
	s_ashr_i32 s62, s88, 31
	v_lshl_add_u64 v[206:207], s[80:81], 0, v[202:203]
	v_mov_b32_e32 v209, v203
	v_add_u32_e32 v210, v1, v9
	v_mov_b32_e32 v211, v203
	v_mov_b64_e32 v[212:213], 0x180
	v_mov_b64_e32 v[214:215], 0x17f
	v_add_u32_e32 v232, s63, v231
	v_add_u32_e32 v233, s64, v231
	v_lshlrev_b32_e32 v216, 2, v204
	v_mov_b32_e32 v235, 0x358637bd
	s_mov_b32 s65, 0xf800000
	v_mov_b32_e32 v236, 0x260
	s_movk_i32 s66, 0xc00
	v_mov_b32_e32 v237, 0x3e38aa3b
	v_mbcnt_hi_u32_b32 v238, -1, v0
	s_barrier
	s_branch .LBB0_765

.LBB0_952:
	v_bfe_u32 v199, v226, 4, 2
	s_lshl_b32 s6, s6, 5
	v_lshlrev_b32_e32 v11, 6, v226
	v_and_b32_e32 v191, 15, v226
	v_lshlrev_b32_e32 v9, 4, v199
	s_and_b32 s19, s6, 0x60
	v_and_b32_e32 v197, 0x3c0, v11
	v_lshl_or_b32 v132, s7, 6, v191
	v_lshl_or_b32 v10, v191, 6, v9
	s_lshl_b32 s7, s7, 13
	v_and_b32_e32 v196, 32, v160
	v_or_b32_e32 v9, v9, v197
	s_lshl_b32 s6, s19, 7
	v_bitop3_b32 v10, v10, s7, v196 bitop3:0xde
	v_bitop3_b32 v9, s6, v9, v196 bitop3:0xf6
	s_mov_b64 s[6:7], 0x80
	s_add_i32 m0, s15, 0x18000
	v_lshl_add_u64 v[6:7], v[6:7], 0, s[6:7]
	global_load_lds_dwordx4 v[6:7], off
	v_lshl_add_u64 v[4:5], v[4:5], 0, s[6:7]
	s_add_i32 m0, s15, 0x1a000
	s_add_i32 s20, s15, 0x8000
	s_add_i32 s21, s15, 0xa000
	global_load_lds_dwordx4 v[4:5], off
	v_lshl_add_u64 v[2:3], v[2:3], 0, s[6:7]
	s_mov_b32 m0, s20
	s_add_u32 s22, s0, 0x40080
	global_load_lds_dwordx4 v[2:3], off
	v_lshl_add_u64 v[0:1], v[0:1], 0, s[6:7]
	s_mov_b32 m0, s21
	s_addc_u32 s23, s1, 0
	global_load_lds_dwordx4 v[0:1], off
	s_add_i32 m0, s15, 0x1c000
	v_lshl_add_u64 v[0:1], s[22:23], 0, v[156:157]
	global_load_lds_dwordx4 v[0:1], off
	v_lshl_add_u64 v[0:1], s[22:23], 0, v[152:153]
	s_add_i32 m0, s15, 0x1e000
	s_lshl_b32 s10, s41, 4
	global_load_lds_dwordx4 v[0:1], off
	s_lshl_b32 s13, s53, 1
	v_lshrrev_b32_e32 v192, 7, v226
	v_readlane_b32 s24, v254, 0
	s_or_b32 s10, s10, s13
	v_lshlrev_b32_e32 v0, 15, v192
	v_lshlrev_b32_e32 v1, 11, v185
	v_readlane_b32 s26, v254, 2
	v_readlane_b32 s27, v254, 3
	s_lshl_b64 s[10:11], s[10:11], 19
	v_or3_b32 v0, v183, v0, v1
	s_mov_b64 s[22:23], s[26:27]
	v_lshrrev_b32_e32 v193, 11, v8
	v_add_u32_e32 v160, v0, v184
	s_add_u32 s10, s22, s10
	v_lshlrev_b32_e32 v0, 15, v193
	s_waitcnt vmcnt(8)
	s_barrier
	s_waitcnt vmcnt(6)
	v_readlane_b32 s25, v254, 1
	s_addc_u32 s11, s23, s11
	v_or3_b32 v0, v183, v0, v1
	s_add_i32 s48, 0, 0x10000
	s_add_i32 s49, 0, 0x14000
	s_add_i32 s51, 0, 0x18000
	s_add_i32 s53, 0, 0x1c000
	v_mov_b32_e32 v161, v157
	v_add_u32_e32 v162, v0, v184
	v_mov_b32_e32 v163, v157
	s_add_i32 s25, s48, s12
	s_add_i32 s27, s49, s12
	s_add_i32 s29, s51, s12
	s_add_i32 s31, s53, s12
	s_mov_b64 s[8:9], 0x40080
	v_lshl_add_u64 v[128:129], s[10:11], 0, v[160:161]
	v_lshl_add_u64 v[130:131], s[10:11], 0, v[162:163]
	s_mov_b32 s22, -2
	v_add_u32_e32 v133, s48, v9
	v_add_u32_e32 v134, s49, v9
	v_add_u32_e32 v135, 0, v10
	s_add_i32 s23, s15, 0xc000
	s_add_i32 s24, s15, 0xe000
	s_add_i32 s26, s25, 0x2000
	s_add_i32 s28, s27, 0x2000
	v_add_u32_e32 v136, s51, v9
	v_add_u32_e32 v137, s53, v9
	s_add_i32 s30, s29, 0x2000
	s_add_i32 s34, s31, 0x2000
	v_mov_b32_e32 v0, v157
	v_mov_b32_e32 v1, v157
	v_mov_b32_e32 v2, v157
	v_mov_b32_e32 v3, v157
	v_mov_b32_e32 v4, v157
	v_mov_b32_e32 v5, v157
	v_mov_b32_e32 v6, v157
	v_mov_b32_e32 v7, v157
	v_mov_b32_e32 v16, v157
	v_mov_b32_e32 v17, v157
	v_mov_b32_e32 v18, v157
	v_mov_b32_e32 v19, v157
	v_mov_b32_e32 v20, v157
	v_mov_b32_e32 v21, v157
	v_mov_b32_e32 v22, v157
	v_mov_b32_e32 v23, v157
	v_mov_b32_e32 v32, v157
	v_mov_b32_e32 v33, v157
	v_mov_b32_e32 v34, v157
	v_mov_b32_e32 v35, v157
	v_mov_b32_e32 v36, v157
	v_mov_b32_e32 v37, v157
	v_mov_b32_e32 v38, v157
	v_mov_b32_e32 v39, v157
	v_mov_b32_e32 v48, v157
	v_mov_b32_e32 v49, v157
	v_mov_b32_e32 v50, v157
	v_mov_b32_e32 v51, v157
	v_mov_b32_e32 v52, v157
	v_mov_b32_e32 v53, v157
	v_mov_b32_e32 v54, v157
	v_mov_b32_e32 v55, v157
	v_mov_b32_e32 v8, v157
	v_mov_b32_e32 v9, v157
	v_mov_b32_e32 v10, v157
	v_mov_b32_e32 v11, v157
	v_mov_b32_e32 v12, v157
	v_mov_b32_e32 v13, v157
	v_mov_b32_e32 v14, v157
	v_mov_b32_e32 v15, v157
	v_mov_b32_e32 v24, v157
	v_mov_b32_e32 v25, v157
	v_mov_b32_e32 v26, v157
	v_mov_b32_e32 v27, v157
	v_mov_b32_e32 v28, v157
	v_mov_b32_e32 v29, v157
	v_mov_b32_e32 v30, v157
	v_mov_b32_e32 v31, v157
	v_mov_b32_e32 v40, v157
	v_mov_b32_e32 v41, v157
	v_mov_b32_e32 v42, v157
	v_mov_b32_e32 v43, v157
	v_mov_b32_e32 v44, v157
	v_mov_b32_e32 v45, v157
	v_mov_b32_e32 v46, v157
	v_mov_b32_e32 v47, v157
	v_mov_b32_e32 v56, v157
	v_mov_b32_e32 v57, v157
	v_mov_b32_e32 v58, v157
	v_mov_b32_e32 v59, v157
	v_mov_b32_e32 v60, v157
	v_mov_b32_e32 v61, v157
	v_mov_b32_e32 v62, v157
	v_mov_b32_e32 v63, v157
	v_mov_b32_e32 v64, v157
	v_mov_b32_e32 v65, v157
	v_mov_b32_e32 v66, v157
	v_mov_b32_e32 v67, v157
	v_mov_b32_e32 v68, v157
	v_mov_b32_e32 v69, v157
	v_mov_b32_e32 v70, v157
	v_mov_b32_e32 v71, v157
	v_mov_b32_e32 v80, v157
	v_mov_b32_e32 v81, v157
	v_mov_b32_e32 v82, v157
	v_mov_b32_e32 v83, v157
	v_mov_b32_e32 v84, v157
	v_mov_b32_e32 v85, v157
	v_mov_b32_e32 v86, v157
	v_mov_b32_e32 v87, v157
	v_mov_b32_e32 v96, v157
	v_mov_b32_e32 v97, v157
	v_mov_b32_e32 v98, v157
	v_mov_b32_e32 v99, v157
	v_mov_b32_e32 v100, v157
	v_mov_b32_e32 v101, v157
	v_mov_b32_e32 v102, v157
	v_mov_b32_e32 v103, v157
	v_mov_b32_e32 v112, v157
	v_mov_b32_e32 v113, v157
	v_mov_b32_e32 v114, v157
	v_mov_b32_e32 v115, v157
	v_mov_b32_e32 v116, v157
	v_mov_b32_e32 v117, v157
	v_mov_b32_e32 v118, v157
	v_mov_b32_e32 v119, v157
	v_mov_b32_e32 v72, v157
	v_mov_b32_e32 v73, v157
	v_mov_b32_e32 v74, v157
	v_mov_b32_e32 v75, v157
	v_mov_b32_e32 v76, v157
	v_mov_b32_e32 v77, v157
	v_mov_b32_e32 v78, v157
	v_mov_b32_e32 v79, v157
	v_mov_b32_e32 v88, v157
	v_mov_b32_e32 v89, v157
	v_mov_b32_e32 v90, v157
	v_mov_b32_e32 v91, v157
	v_mov_b32_e32 v92, v157
	v_mov_b32_e32 v93, v157
	v_mov_b32_e32 v94, v157
	v_mov_b32_e32 v95, v157
	v_mov_b32_e32 v104, v157
	v_mov_b32_e32 v105, v157
	v_mov_b32_e32 v106, v157
	v_mov_b32_e32 v107, v157
	v_mov_b32_e32 v108, v157
	v_mov_b32_e32 v109, v157
	v_mov_b32_e32 v110, v157
	v_mov_b32_e32 v111, v157
	v_mov_b32_e32 v120, v157
	v_mov_b32_e32 v121, v157
	v_mov_b32_e32 v122, v157
	v_mov_b32_e32 v123, v157
	v_mov_b32_e32 v124, v157
	v_mov_b32_e32 v125, v157
	v_mov_b32_e32 v126, v157
	v_mov_b32_e32 v127, v157
	s_barrier

.LBB0_990:
	s_lshl_b32 s4, s4, 5
	s_and_b32 s26, s4, 0x60
	s_lshl_b32 s52, s52, 2
	s_lshl_b32 s24, s1, 13
	s_lshl_b32 s25, s26, 7
	s_lshl_b64 s[12:13], s[40:41], 21
	s_sub_u32 s4, 0, s12
	s_subb_u32 s5, 0, s13
	s_add_u32 s14, s44, s4
	s_mov_b64 s[22:23], 0x80
	s_addc_u32 s15, s45, s5
	s_add_i32 m0, s58, 0x18000
	v_lshl_add_u64 v[0:1], v[0:1], 0, s[22:23]
	global_load_lds_dwordx4 v[0:1], off
	v_lshl_add_u64 v[0:1], v[2:3], 0, s[22:23]
	s_add_i32 m0, s58, 0x1a000
	s_add_i32 s62, s58, 0x8000
	s_add_i32 s63, s58, 0xa000
	global_load_lds_dwordx4 v[0:1], off
	v_lshl_add_u64 v[0:1], v[6:7], 0, s[22:23]
	s_mov_b32 m0, s62
	s_add_u32 s4, s16, 0x40080
	global_load_lds_dwordx4 v[0:1], off
	v_lshl_add_u64 v[0:1], v[4:5], 0, s[22:23]
	s_mov_b32 m0, s63
	s_addc_u32 s5, s17, 0
	global_load_lds_dwordx4 v[0:1], off
	s_add_i32 m0, s58, 0x1c000
	v_lshl_add_u64 v[0:1], s[4:5], 0, v[156:157]
	global_load_lds_dwordx4 v[0:1], off
	v_lshl_add_u64 v[0:1], s[4:5], 0, v[152:153]
	s_add_i32 m0, s58, 0x1e000
	s_cmpk_lt_u32 s0, 0x100
	global_load_lds_dwordx4 v[0:1], off
	v_lshlrev_b32_e32 v0, 1, v182
	v_lshlrev_b32_e32 v1, 2, v191
	v_lshl_or_b32 v138, v191, 6, v0
	v_and_b32_e32 v140, 32, v1
	v_or_b32_e32 v2, v0, v197
	s_waitcnt vmcnt(8)
	v_and_b32_e32 v250, 0xff, v226
	v_lshlrev_b32_e32 v250, 2, v250
	v_add_u32_e32 v250, 0x20200, v250
	ds_write_b32 v250, v251
	v_mov_b32_e32 v252, 0x20200
	s_waitcnt lgkmcnt(0)
	s_barrier
	s_waitcnt vmcnt(6)
	v_bitop3_b32 v1, v138, s24, v140 bitop3:0xde
	v_bitop3_b32 v142, s25, v2, v196 bitop3:0xf6
	v_lshl_or_b32 v141, s1, 6, v191
	v_bitop3_b32 v139, v0, v196, v197 bitop3:0x36
	s_cselect_b64 s[24:25], -1, 0
	v_or_b32_e32 v143, s26, v182
	v_add_u32_e32 v144, s48, v142
	v_add_u32_e32 v145, s49, v142
	v_add_u32_e32 v146, 0, v1
	v_mov_b32_e32 v147, 0x358637bd
	s_mov_b32 s64, 0xf800000
	v_mov_b32_e32 v148, 0x260
	s_mov_b64 s[26:27], 0x100000
	s_mov_b32 s65, 0x100000
	s_mov_b64 s[28:29], 0x120000
	s_mov_b32 s66, 0x120000
	s_mov_b64 s[30:31], 0x140000
	s_mov_b32 s67, 0x140000
	s_mov_b64 s[34:35], 0x160000
	s_mov_b32 s68, 0x160000
	s_mov_b32 s36, s52
	s_mov_b32 s42, s40
	s_barrier
	s_branch .LBB0_993

.LBB0_1016:
	v_lshl_or_b32 v141, s5, 6, v191
	s_lshl_b32 s5, s5, 13
	s_lshl_b32 s4, s4, 5
	v_bitop3_b32 v8, v138, s5, v140 bitop3:0xde
	s_and_b32 s21, s4, 0x60
	s_mov_b64 s[4:5], 0x80
	s_add_i32 m0, s17, 0x18000
	v_lshl_add_u64 v[6:7], v[6:7], 0, s[4:5]
	global_load_lds_dwordx4 v[6:7], off
	v_lshl_add_u64 v[4:5], v[4:5], 0, s[4:5]
	s_add_i32 m0, s17, 0x1a000
	s_add_i32 s22, s17, 0x8000
	s_add_i32 s23, s17, 0xa000
	global_load_lds_dwordx4 v[4:5], off
	v_lshl_add_u64 v[2:3], v[2:3], 0, s[4:5]
	s_mov_b32 m0, s22
	s_add_u32 s10, s0, 0x100080
	global_load_lds_dwordx4 v[2:3], off
	v_lshl_add_u64 v[0:1], v[0:1], 0, s[4:5]
	s_mov_b32 m0, s23
	s_addc_u32 s11, s1, 0
	global_load_lds_dwordx4 v[0:1], off
	s_add_i32 m0, s17, 0x1c000
	v_lshl_add_u64 v[0:1], s[10:11], 0, v[132:133]
	global_load_lds_dwordx4 v[0:1], off
	v_lshl_add_u64 v[0:1], s[10:11], 0, v[128:129]
	s_add_i32 m0, s17, 0x1e000
	s_add_u32 s10, s44, 0x100080
	global_load_lds_dwordx4 v[0:1], off
	s_addc_u32 s11, s45, 0
	v_lshlrev_b32_e32 v0, 17, v192
	v_lshlrev_b32_e32 v1, 13, v185
	s_add_u32 s12, s96, s54
	v_or3_b32 v0, v183, v0, v1
	s_addc_u32 s13, s97, 0
	s_waitcnt vmcnt(8)
	s_barrier
	s_waitcnt vmcnt(6)
	v_add_u32_e32 v136, v0, v184
	v_lshlrev_b32_e32 v0, 17, v193
	s_add_u32 s24, s12, 0x2100100
	v_lshl_or_b32 v9, s21, 7, v139
	v_or3_b32 v0, v183, v0, v1
	s_addc_u32 s25, s13, 0
	s_add_i32 s29, s48, s37
	s_add_i32 s31, s49, s37
	s_add_i32 s35, s51, s37
	s_add_i32 s37, s53, s37
	v_mov_b32_e32 v137, v133
	v_add_u32_e32 v138, v0, v184
	v_mov_b32_e32 v139, v133
	s_mov_b32 s26, -2
	v_add_u32_e32 v140, s48, v9
	v_add_u32_e32 v142, s49, v9
	v_add_u32_e32 v143, 0, v8
	s_add_i32 s27, s17, 0xc000
	s_add_i32 s28, s17, 0xe000
	s_add_i32 s30, s29, 0x2000
	s_add_i32 s34, s31, 0x2000
	v_add_u32_e32 v144, s51, v9
	v_add_u32_e32 v145, s53, v9
	s_add_i32 s36, s35, 0x2000
	s_add_i32 s38, s37, 0x2000
	v_mov_b32_e32 v0, v133
	v_mov_b32_e32 v1, v133
	v_mov_b32_e32 v2, v133
	v_mov_b32_e32 v3, v133
	v_mov_b32_e32 v4, v133
	v_mov_b32_e32 v5, v133
	v_mov_b32_e32 v6, v133
	v_mov_b32_e32 v7, v133
	v_mov_b32_e32 v12, v133
	v_mov_b32_e32 v13, v133
	v_mov_b32_e32 v14, v133
	v_mov_b32_e32 v15, v133
	v_mov_b32_e32 v20, v133
	v_mov_b32_e32 v21, v133
	v_mov_b32_e32 v22, v133
	v_mov_b32_e32 v23, v133
	v_mov_b32_e32 v28, v133
	v_mov_b32_e32 v29, v133
	v_mov_b32_e32 v30, v133
	v_mov_b32_e32 v31, v133
	v_mov_b32_e32 v36, v133
	v_mov_b32_e32 v37, v133
	v_mov_b32_e32 v38, v133
	v_mov_b32_e32 v39, v133
	v_mov_b32_e32 v44, v133
	v_mov_b32_e32 v45, v133
	v_mov_b32_e32 v46, v133
	v_mov_b32_e32 v47, v133
	v_mov_b32_e32 v52, v133
	v_mov_b32_e32 v53, v133
	v_mov_b32_e32 v54, v133
	v_mov_b32_e32 v55, v133
	v_mov_b32_e32 v8, v133
	v_mov_b32_e32 v9, v133
	v_mov_b32_e32 v10, v133
	v_mov_b32_e32 v11, v133
	v_mov_b32_e32 v16, v133
	v_mov_b32_e32 v17, v133
	v_mov_b32_e32 v18, v133
	v_mov_b32_e32 v19, v133
	v_mov_b32_e32 v24, v133
	v_mov_b32_e32 v25, v133
	v_mov_b32_e32 v26, v133
	v_mov_b32_e32 v27, v133
	v_mov_b32_e32 v32, v133
	v_mov_b32_e32 v33, v133
	v_mov_b32_e32 v34, v133
	v_mov_b32_e32 v35, v133
	v_mov_b32_e32 v40, v133
	v_mov_b32_e32 v41, v133
	v_mov_b32_e32 v42, v133
	v_mov_b32_e32 v43, v133
	v_mov_b32_e32 v48, v133
	v_mov_b32_e32 v49, v133
	v_mov_b32_e32 v50, v133
	v_mov_b32_e32 v51, v133
	v_mov_b32_e32 v56, v133
	v_mov_b32_e32 v57, v133
	v_mov_b32_e32 v58, v133
	v_mov_b32_e32 v59, v133
	v_mov_b32_e32 v60, v133
	v_mov_b32_e32 v61, v133
	v_mov_b32_e32 v62, v133
	v_mov_b32_e32 v63, v133
	v_mov_b32_e32 v64, v133
	v_mov_b32_e32 v65, v133
	v_mov_b32_e32 v66, v133
	v_mov_b32_e32 v67, v133
	v_mov_b32_e32 v68, v133
	v_mov_b32_e32 v69, v133
	v_mov_b32_e32 v70, v133
	v_mov_b32_e32 v71, v133
	v_mov_b32_e32 v76, v133
	v_mov_b32_e32 v77, v133
	v_mov_b32_e32 v78, v133
	v_mov_b32_e32 v79, v133
	v_mov_b32_e32 v84, v133
	v_mov_b32_e32 v85, v133
	v_mov_b32_e32 v86, v133
	v_mov_b32_e32 v87, v133
	v_mov_b32_e32 v92, v133
	v_mov_b32_e32 v93, v133
	v_mov_b32_e32 v94, v133
	v_mov_b32_e32 v95, v133
	v_mov_b32_e32 v100, v133
	v_mov_b32_e32 v101, v133
	v_mov_b32_e32 v102, v133
	v_mov_b32_e32 v103, v133
	v_mov_b32_e32 v108, v133
	v_mov_b32_e32 v109, v133
	v_mov_b32_e32 v110, v133
	v_mov_b32_e32 v111, v133
	v_mov_b32_e32 v116, v133
	v_mov_b32_e32 v117, v133
	v_mov_b32_e32 v118, v133
	v_mov_b32_e32 v119, v133
	v_mov_b32_e32 v72, v133
	v_mov_b32_e32 v73, v133
	v_mov_b32_e32 v74, v133
	v_mov_b32_e32 v75, v133
	v_mov_b32_e32 v80, v133
	v_mov_b32_e32 v81, v133
	v_mov_b32_e32 v82, v133
	v_mov_b32_e32 v83, v133
	v_mov_b32_e32 v88, v133
	v_mov_b32_e32 v89, v133
	v_mov_b32_e32 v90, v133
	v_mov_b32_e32 v91, v133
	v_mov_b32_e32 v96, v133
	v_mov_b32_e32 v97, v133
	v_mov_b32_e32 v98, v133
	v_mov_b32_e32 v99, v133
	v_mov_b32_e32 v104, v133
	v_mov_b32_e32 v105, v133
	v_mov_b32_e32 v106, v133
	v_mov_b32_e32 v107, v133
	v_mov_b32_e32 v112, v133
	v_mov_b32_e32 v113, v133
	v_mov_b32_e32 v114, v133
	v_mov_b32_e32 v115, v133
	v_mov_b32_e32 v120, v133
	v_mov_b32_e32 v121, v133
	v_mov_b32_e32 v122, v133
	v_mov_b32_e32 v123, v133
	v_mov_b32_e32 v124, v133
	v_mov_b32_e32 v125, v133
	v_mov_b32_e32 v126, v133
	v_mov_b32_e32 v127, v133
	s_barrier
